# v20: attention dequeue atomic no longer waits for the wave's output stores to drain first
# baseline (speedup 1.0000x reference)
.LBB0_173:
	s_mov_b64 s[4:5], exec
	v_readlane_b32 s6, v253, 7
	v_readlane_b32 s7, v253, 8
	s_and_b64 s[6:7], s[4:5], s[6:7]
	s_mov_b64 exec, s[6:7]
	s_cbranch_execz .LBB0_175
	v_readlane_b32 s6, v255, 32
	v_readlane_b32 s7, v255, 33
	s_nop 0
	s_nop 0
	v_mov_b64_e32 v[0:1], s[6:7]
	flat_atomic_add v0, v[0:1], v232 offset:256 sc0
	s_waitcnt vmcnt(0) lgkmcnt(0)
	ds_write_b32 v129, v0 offset:63680
